# v52: v51 + passB unit tails load the four head-norm weight segments once (v56..v71) instead of 16 dependent load/wait round trips per unit
# speedup vs baseline: 1.0057x; 1.0003x over previous
; #define LAS __attribute__((address_space(3)))
; __device__ __forceinline__ unsigned cvt_pk_bf16(float lo, float hi) { unsigned r; asm volatile("v_cvt_pk_bf16_f32 %0, %1, %2" : "=v"(r) : "v"(lo), "v"(hi)); return r; }
; __device__ void passB_unit(const Params& p, LAS unsigned char* lds, int u, bool do_store = true) {
;     ...
; #pragma unroll
;     for (int mt = 0; mt < 4; ++mt) { const int t = wt2 * 64 + mt * 16 + fr;
;         const float tot = (ssP[t] + ssP[128 + t]) + (ssP[256 + t] + ssP[384 + t]); const float rinv = rsqrtf(tot * (1.0f / 256.0f) + 1e-6f);
; #pragma unroll
;         for (int nt = 0; nt < 4; ++nt) { const int v = w4 * 64 + nt * 16 + fq * 4; const f32x4 hw = *(const f32x4*)(p.head_norm_w + h * 256 + v);
;             const f32x4 o = hsum[mt][nt] * rinv * hw;
;             u32x2 w; w.x = cvt_pk_bf16(o[0], o[1]); w.y = cvt_pk_bf16(o[2], o[3]);
;             *(LAS u32x2*)(Pd + t * 264 + v) = w; } }
.LBB0_567:
	s_or_b64 exec, exec, s[0:1]
	v_readlane_b32 s80, v254, 6
	v_readlane_b32 s82, v254, 8
	v_readlane_b32 s83, v254, 9
	s_lshl_b32 s0, s34, 10
	s_mov_b64 s[54:55], s[82:83]
	v_lshl_or_b32 v50, v223, 6, v212
	s_add_u32 s42, s54, s0
	s_addc_u32 s43, s55, 0
	v_lshlrev_b32_e32 v52, 2, v50
	s_waitcnt lgkmcnt(0)
	s_barrier
	global_load_dwordx4 v[56:59], v52, s[42:43]
	global_load_dwordx4 v[60:63], v52, s[42:43] offset:64
	global_load_dwordx4 v[64:67], v52, s[42:43] offset:128
	global_load_dwordx4 v[68:71], v52, s[42:43] offset:192
	v_lshl_add_u32 v38, v211, 2, s49
	ds_read2st64_b32 v[36:37], v38 offset1:2
	ds_read2st64_b32 v[38:39], v38 offset0:4 offset1:6
	v_mov_b32_e32 v53, 0x358637bd
	s_mov_b32 s0, 0x800000
	v_lshlrev_b32_e32 v54, 1, v50
	s_waitcnt lgkmcnt(1)
	v_mov_b32_e32 v48, v36
	s_waitcnt lgkmcnt(0)
	v_mov_b32_e32 v49, v38
	v_mov_b32_e32 v38, v37
	v_pk_add_f32 v[36:37], v[48:49], v[38:39]
	v_add3_u32 v55, s46, v210, v54
	v_add_f32_e32 v36, v36, v37
	v_fmamk_f32 v36, v36, 0x3b800000, v53
	v_mul_f32_e32 v37, 0x4b800000, v36
	v_cmp_gt_f32_e32 vcc, s0, v36
	v_readlane_b32 s81, v254, 7
	v_readlane_b32 s84, v254, 10
	v_cndmask_b32_e32 v36, v36, v37, vcc
	v_rsq_f32_e32 v36, v36
	v_readlane_b32 s85, v254, 11
	v_readlane_b32 s86, v254, 12
	v_readlane_b32 s87, v254, 13
	v_mul_f32_e32 v37, 0x45800000, v36
	v_cndmask_b32_e32 v36, v36, v37, vcc
	v_pk_mul_f32 v[38:39], v[186:187], v[36:37] op_sel_hi:[1,0]
	v_pk_mul_f32 v[48:49], v[184:185], v[36:37] op_sel_hi:[1,0]
	v_pk_mul_f32 v[50:51], v[180:181], v[36:37] op_sel_hi:[1,0]
	v_readlane_b32 s88, v254, 14
	v_readlane_b32 s89, v254, 15
	v_readlane_b32 s90, v254, 16
	v_readlane_b32 s91, v254, 17
	v_readlane_b32 s92, v254, 18
	v_readlane_b32 s93, v254, 19
	v_readlane_b32 s94, v254, 20
	v_readlane_b32 s95, v254, 21
	s_waitcnt vmcnt(0)
	v_pk_mul_f32 v[26:27], v[58:59], v[48:49]
	v_pk_mul_f32 v[24:25], v[56:57], v[38:39]
	v_pk_mul_f32 v[48:49], v[182:183], v[36:37] op_sel_hi:[1,0]
	v_cvt_pk_bf16_f32 v38, v24, v25
	v_cvt_pk_bf16_f32 v39, v26, v27
	ds_write_b64 v55, v[38:39]
	s_waitcnt vmcnt(0)
	v_pk_mul_f32 v[26:27], v[62:63], v[50:51]
	v_pk_mul_f32 v[24:25], v[60:61], v[48:49]
	v_pk_mul_f32 v[48:49], v[106:107], v[36:37] op_sel_hi:[1,0]
	v_cvt_pk_bf16_f32 v38, v24, v25
	v_cvt_pk_bf16_f32 v39, v26, v27
	v_pk_mul_f32 v[50:51], v[104:105], v[36:37] op_sel_hi:[1,0]
	ds_write_b64 v55, v[38:39] offset:32
	s_waitcnt vmcnt(0)
	v_pk_mul_f32 v[26:27], v[66:67], v[50:51]
	v_pk_mul_f32 v[24:25], v[64:65], v[48:49]
	v_pk_mul_f32 v[48:49], v[98:99], v[36:37] op_sel_hi:[1,0]
	v_cvt_pk_bf16_f32 v38, v24, v25
	v_cvt_pk_bf16_f32 v39, v26, v27
	v_pk_mul_f32 v[36:37], v[96:97], v[36:37] op_sel_hi:[1,0]
	ds_write_b64 v55, v[38:39] offset:64
	v_lshl_add_u32 v38, v213, 2, s49
	s_waitcnt vmcnt(0)
	v_pk_mul_f32 v[26:27], v[36:37], v[70:71]
	v_pk_mul_f32 v[24:25], v[48:49], v[68:69]
	s_nop 0
	v_cvt_pk_bf16_f32 v36, v24, v25
	v_cvt_pk_bf16_f32 v37, v26, v27
	ds_write_b64 v55, v[36:37] offset:96
	ds_read2st64_b32 v[36:37], v38 offset1:2
	ds_read2st64_b32 v[38:39], v38 offset0:4 offset1:6
	v_add3_u32 v55, s46, v253, v54
	s_waitcnt lgkmcnt(1)
	v_mov_b32_e32 v48, v36
	s_waitcnt lgkmcnt(0)
	v_mov_b32_e32 v49, v38
	v_mov_b32_e32 v38, v37
	v_pk_add_f32 v[36:37], v[48:49], v[38:39]
	s_nop 0
	v_add_f32_e32 v36, v36, v37
	v_fmamk_f32 v36, v36, 0x3b800000, v53
	v_mul_f32_e32 v37, 0x4b800000, v36
	v_cmp_gt_f32_e32 vcc, s0, v36
	s_nop 1
	v_cndmask_b32_e32 v36, v36, v37, vcc
	v_rsq_f32_e32 v36, v36
	s_nop 0
	v_mul_f32_e32 v37, 0x45800000, v36
	v_cndmask_b32_e32 v36, v36, v37, vcc
	v_pk_mul_f32 v[38:39], v[110:111], v[36:37] op_sel_hi:[1,0]
	v_pk_mul_f32 v[48:49], v[108:109], v[36:37] op_sel_hi:[1,0]
	v_pk_mul_f32 v[50:51], v[100:101], v[36:37] op_sel_hi:[1,0]
	v_pk_mul_f32 v[46:47], v[46:47], v[36:37] op_sel_hi:[1,0]
	v_pk_mul_f32 v[44:45], v[44:45], v[36:37] op_sel_hi:[1,0]
	v_pk_mul_f32 v[42:43], v[42:43], v[36:37] op_sel_hi:[1,0]
	s_waitcnt vmcnt(0)
	v_pk_mul_f32 v[26:27], v[58:59], v[48:49]
	v_pk_mul_f32 v[24:25], v[56:57], v[38:39]
	v_pk_mul_f32 v[48:49], v[102:103], v[36:37] op_sel_hi:[1,0]
	v_cvt_pk_bf16_f32 v38, v24, v25
	v_cvt_pk_bf16_f32 v39, v26, v27
	ds_write_b64 v55, v[38:39]
	v_pk_mul_f32 v[36:37], v[40:41], v[36:37] op_sel_hi:[1,0]
	s_waitcnt vmcnt(0)
	v_pk_mul_f32 v[26:27], v[62:63], v[50:51]
	v_pk_mul_f32 v[24:25], v[60:61], v[48:49]
	s_nop 0
	v_cvt_pk_bf16_f32 v38, v24, v25
	v_cvt_pk_bf16_f32 v39, v26, v27
	ds_write_b64 v55, v[38:39] offset:32
	s_waitcnt vmcnt(0)
; #define LAS __attribute__((address_space(3)))
; __device__ __forceinline__ unsigned cvt_pk_bf16(float lo, float hi) { unsigned r; asm volatile("v_cvt_pk_bf16_f32 %0, %1, %2" : "=v"(r) : "v"(lo), "v"(hi)); return r; }
; __device__ void passB_unit(const Params& p, LAS unsigned char* lds, int u, bool do_store = true) {
;     ...
; #pragma unroll
;     for (int mt = 0; mt < 4; ++mt) { const int t = wt2 * 64 + mt * 16 + fr;
;         const float tot = (ssP[t] + ssP[128 + t]) + (ssP[256 + t] + ssP[384 + t]); const float rinv = rsqrtf(tot * (1.0f / 256.0f) + 1e-6f);
; #pragma unroll
;         for (int nt = 0; nt < 4; ++nt) { const int v = w4 * 64 + nt * 16 + fq * 4; const f32x4 hw = *(const f32x4*)(p.head_norm_w + h * 256 + v);
;             const f32x4 o = hsum[mt][nt] * rinv * hw;
;             u32x2 w; w.x = cvt_pk_bf16(o[0], o[1]); w.y = cvt_pk_bf16(o[2], o[3]);
;             *(LAS u32x2*)(Pd + t * 264 + v) = w; } }
	v_pk_mul_f32 v[26:27], v[66:67], v[44:45]
	v_pk_mul_f32 v[24:25], v[64:65], v[46:47]
	s_nop 0
	v_cvt_pk_bf16_f32 v38, v24, v25
	v_cvt_pk_bf16_f32 v39, v26, v27
	ds_write_b64 v55, v[38:39] offset:64
	v_lshl_add_u32 v38, v214, 2, s49
	s_waitcnt vmcnt(0)
	v_pk_mul_f32 v[26:27], v[36:37], v[70:71]
	v_pk_mul_f32 v[24:25], v[42:43], v[68:69]
	s_nop 0
	v_cvt_pk_bf16_f32 v36, v24, v25
	v_cvt_pk_bf16_f32 v37, v26, v27
	ds_write_b64 v55, v[36:37] offset:96
	ds_read2st64_b32 v[36:37], v38 offset1:2
	ds_read2st64_b32 v[38:39], v38 offset0:4 offset1:6
	s_waitcnt lgkmcnt(1)
	v_mov_b32_e32 v40, v36
	s_waitcnt lgkmcnt(0)
	v_mov_b32_e32 v41, v38
	v_mov_b32_e32 v38, v37
	v_pk_add_f32 v[36:37], v[40:41], v[38:39]
	s_nop 0
	v_add_f32_e32 v36, v36, v37
	v_fmamk_f32 v36, v36, 0x3b800000, v53
	v_mul_f32_e32 v37, 0x4b800000, v36
	v_cmp_gt_f32_e32 vcc, s0, v36
	s_nop 1
	v_cndmask_b32_e32 v36, v36, v37, vcc
	v_rsq_f32_e32 v36, v36
	s_nop 0
	v_mul_f32_e32 v37, 0x45800000, v36
	v_cndmask_b32_e32 v36, v36, v37, vcc
	v_pk_mul_f32 v[32:33], v[32:33], v[36:37] op_sel_hi:[1,0]
	v_pk_mul_f32 v[34:35], v[34:35], v[36:37] op_sel_hi:[1,0]
	v_pk_mul_f32 v[22:23], v[22:23], v[36:37] op_sel_hi:[1,0]
	v_pk_mul_f32 v[20:21], v[20:21], v[36:37] op_sel_hi:[1,0]
	v_pk_mul_f32 v[18:19], v[18:19], v[36:37] op_sel_hi:[1,0]
	v_pk_mul_f32 v[14:15], v[14:15], v[36:37] op_sel_hi:[1,0]
	v_pk_mul_f32 v[10:11], v[10:11], v[36:37] op_sel_hi:[1,0]
	v_pk_mul_f32 v[8:9], v[8:9], v[36:37] op_sel_hi:[1,0]
	s_waitcnt vmcnt(0)
	v_pk_mul_f32 v[26:27], v[58:59], v[34:35]
	v_pk_mul_f32 v[24:25], v[56:57], v[32:33]
	v_add3_u32 v34, s46, v252, v54
	v_cvt_pk_bf16_f32 v32, v24, v25
	v_cvt_pk_bf16_f32 v33, v26, v27
	ds_write_b64 v34, v[32:33]
	s_waitcnt vmcnt(0)
	v_pk_mul_f32 v[20:21], v[62:63], v[20:21]
	v_pk_mul_f32 v[22:23], v[60:61], v[22:23]
	s_nop 0
	v_cvt_pk_bf16_f32 v24, v22, v23
	v_cvt_pk_bf16_f32 v25, v20, v21
	ds_write_b64 v34, v[24:25] offset:32
	s_waitcnt vmcnt(0)
	v_pk_mul_f32 v[18:19], v[64:65], v[18:19]
	v_pk_mul_f32 v[14:15], v[66:67], v[14:15]
	v_cvt_pk_bf16_f32 v22, v18, v19
	s_nop 0
	v_cvt_pk_bf16_f32 v23, v14, v15
	ds_write_b64 v34, v[22:23] offset:64
	s_waitcnt vmcnt(0)
	v_pk_mul_f32 v[8:9], v[8:9], v[70:71]
	v_pk_mul_f32 v[10:11], v[10:11], v[68:69]
	v_lshl_add_u32 v18, v215, 2, s49
	v_cvt_pk_bf16_f32 v14, v10, v11
	v_cvt_pk_bf16_f32 v15, v8, v9
	ds_write_b64 v34, v[14:15] offset:96
	ds_read2st64_b32 v[14:15], v18 offset1:2
	ds_read2st64_b32 v[18:19], v18 offset0:4 offset1:6
	s_waitcnt lgkmcnt(1)
	v_mov_b32_e32 v20, v14
	s_waitcnt lgkmcnt(0)
	v_mov_b32_e32 v21, v18
	v_mov_b32_e32 v18, v15
	v_pk_add_f32 v[14:15], v[20:21], v[18:19]
	s_nop 0
	v_add_f32_e32 v14, v14, v15
	v_fmac_f32_e32 v53, 0x3b800000, v14
	v_mul_f32_e32 v14, 0x4b800000, v53
	v_cmp_gt_f32_e32 vcc, s0, v53
	s_mov_b32 s0, 0
	s_nop 0
	v_cndmask_b32_e32 v14, v53, v14, vcc
	v_rsq_f32_e32 v14, v14
	s_nop 0
	v_mul_f32_e32 v15, 0x45800000, v14
	v_cndmask_b32_e32 v14, v14, v15, vcc
	v_pk_mul_f32 v[18:19], v[28:29], v[14:15] op_sel_hi:[1,0]
	v_pk_mul_f32 v[20:21], v[30:31], v[14:15] op_sel_hi:[1,0]
	v_add3_u32 v15, s46, v227, v54
	v_pk_mul_f32 v[16:17], v[16:17], v[14:15] op_sel_hi:[1,0]
	v_pk_mul_f32 v[6:7], v[6:7], v[14:15] op_sel_hi:[1,0]
	v_pk_mul_f32 v[12:13], v[12:13], v[14:15] op_sel_hi:[1,0]
	v_pk_mul_f32 v[4:5], v[4:5], v[14:15] op_sel_hi:[1,0]
	v_pk_mul_f32 v[2:3], v[2:3], v[14:15] op_sel_hi:[1,0]
	v_pk_mul_f32 v[0:1], v[0:1], v[14:15] op_sel_hi:[1,0]
	s_waitcnt vmcnt(0)
	v_pk_mul_f32 v[10:11], v[58:59], v[20:21]
	v_pk_mul_f32 v[8:9], v[56:57], v[18:19]
	s_nop 0
	v_cvt_pk_bf16_f32 v18, v8, v9
	v_cvt_pk_bf16_f32 v19, v10, v11
	ds_write_b64 v15, v[18:19]
	s_waitcnt vmcnt(0)
	v_pk_mul_f32 v[6:7], v[62:63], v[6:7]
	v_pk_mul_f32 v[8:9], v[60:61], v[16:17]
	s_nop 0
	v_cvt_pk_bf16_f32 v10, v8, v9
	v_cvt_pk_bf16_f32 v11, v6, v7
	ds_write_b64 v15, v[10:11] offset:32
	s_waitcnt vmcnt(0)
	v_pk_mul_f32 v[4:5], v[66:67], v[4:5]
	v_pk_mul_f32 v[6:7], v[64:65], v[12:13]
	s_nop 0
	v_cvt_pk_bf16_f32 v8, v6, v7
	v_cvt_pk_bf16_f32 v9, v4, v5
	ds_write_b64 v15, v[8:9] offset:64
	s_waitcnt vmcnt(0)
	v_pk_mul_f32 v[0:1], v[0:1], v[70:71]
	v_pk_mul_f32 v[2:3], v[2:3], v[68:69]
	s_nop 0
	v_cvt_pk_bf16_f32 v2, v2, v3
	v_cvt_pk_bf16_f32 v3, v0, v1
	ds_write_b64 v15, v[2:3] offset:96
	s_waitcnt lgkmcnt(0)
	s_barrier
	v_or_b32_e32 v2, v198, v199
	v_add_u32_e32 v0, s46, v203
	v_or_b32_e32 v1, v202, v201
	s_mov_b32 s1, 0xfffffc0
	s_movk_i32 s4, 0x210
	v_lshlrev_b32_e32 v2, 6, v2

; #define LAS __attribute__((address_space(3)))
; __device__ __forceinline__ unsigned cvt_pk_bf16(float lo, float hi) { unsigned r; asm volatile("v_cvt_pk_bf16_f32 %0, %1, %2" : "=v"(r) : "v"(lo), "v"(hi)); return r; }
; __device__ void passB_unit(const Params& p, LAS unsigned char* lds, int u, bool do_store = true) {
;     ...
; #pragma unroll
;     for (int mt = 0; mt < 4; ++mt) { const int t = wt2 * 64 + mt * 16 + fr;
;         const float tot = (ssP[t] + ssP[128 + t]) + (ssP[256 + t] + ssP[384 + t]); const float rinv = rsqrtf(tot * (1.0f / 256.0f) + 1e-6f);
; #pragma unroll
;         for (int nt = 0; nt < 4; ++nt) { const int v = w4 * 64 + nt * 16 + fq * 4; const f32x4 hw = *(const f32x4*)(p.head_norm_w + h * 256 + v);
;             const f32x4 o = hsum[mt][nt] * rinv * hw;
;             u32x2 w; w.x = cvt_pk_bf16(o[0], o[1]); w.y = cvt_pk_bf16(o[2], o[3]);
;             *(LAS u32x2*)(Pd + t * 264 + v) = w; } }
.LBB0_603:
	s_or_b64 exec, exec, s[0:1]
	v_lshl_or_b32 v50, v221, 6, v210
	v_lshlrev_b32_e32 v52, 2, v50
	s_waitcnt lgkmcnt(0)
	s_barrier
	global_load_dwordx4 v[56:59], v52, s[42:43]
	global_load_dwordx4 v[60:63], v52, s[42:43] offset:64
	global_load_dwordx4 v[64:67], v52, s[42:43] offset:128
	global_load_dwordx4 v[68:71], v52, s[42:43] offset:192
	v_lshl_add_u32 v38, v209, 2, s49
	ds_read2st64_b32 v[36:37], v38 offset1:2
	ds_read2st64_b32 v[38:39], v38 offset0:4 offset1:6
	v_mov_b32_e32 v53, 0x358637bd
	s_mov_b32 s0, 0x800000
	v_lshlrev_b32_e32 v54, 1, v50
	s_waitcnt lgkmcnt(1)
	v_mov_b32_e32 v48, v36
	s_waitcnt lgkmcnt(0)
	v_mov_b32_e32 v49, v38
	v_mov_b32_e32 v38, v37
	v_pk_add_f32 v[36:37], v[48:49], v[38:39]
	v_add3_u32 v55, s46, v208, v54
	v_add_f32_e32 v36, v36, v37
	v_fmamk_f32 v36, v36, 0x3b800000, v53
	v_mul_f32_e32 v37, 0x4b800000, v36
	v_cmp_gt_f32_e32 vcc, s0, v36
	s_nop 1
	v_cndmask_b32_e32 v36, v36, v37, vcc
	v_rsq_f32_e32 v36, v36
	s_nop 0
	v_mul_f32_e32 v37, 0x45800000, v36
	v_cndmask_b32_e32 v36, v36, v37, vcc
	v_pk_mul_f32 v[38:39], v[186:187], v[36:37] op_sel_hi:[1,0]
	v_pk_mul_f32 v[48:49], v[184:185], v[36:37] op_sel_hi:[1,0]
	v_pk_mul_f32 v[50:51], v[180:181], v[36:37] op_sel_hi:[1,0]
	s_waitcnt vmcnt(0)
	v_pk_mul_f32 v[26:27], v[58:59], v[48:49]
	v_pk_mul_f32 v[24:25], v[56:57], v[38:39]
	v_pk_mul_f32 v[48:49], v[182:183], v[36:37] op_sel_hi:[1,0]
	v_cvt_pk_bf16_f32 v38, v24, v25
	v_cvt_pk_bf16_f32 v39, v26, v27
	ds_write_b64 v55, v[38:39]
	s_waitcnt vmcnt(0)
	v_pk_mul_f32 v[26:27], v[62:63], v[50:51]
	v_pk_mul_f32 v[24:25], v[60:61], v[48:49]
	v_pk_mul_f32 v[48:49], v[106:107], v[36:37] op_sel_hi:[1,0]
	v_cvt_pk_bf16_f32 v38, v24, v25
	v_cvt_pk_bf16_f32 v39, v26, v27
	v_pk_mul_f32 v[50:51], v[104:105], v[36:37] op_sel_hi:[1,0]
	ds_write_b64 v55, v[38:39] offset:32
	s_waitcnt vmcnt(0)
	v_pk_mul_f32 v[26:27], v[66:67], v[50:51]
	v_pk_mul_f32 v[24:25], v[64:65], v[48:49]
	v_pk_mul_f32 v[48:49], v[100:101], v[36:37] op_sel_hi:[1,0]
	v_cvt_pk_bf16_f32 v38, v24, v25
	v_cvt_pk_bf16_f32 v39, v26, v27
	v_pk_mul_f32 v[36:37], v[96:97], v[36:37] op_sel_hi:[1,0]
	ds_write_b64 v55, v[38:39] offset:64
	v_lshl_add_u32 v38, v211, 2, s49
	s_waitcnt vmcnt(0)
	v_pk_mul_f32 v[26:27], v[36:37], v[70:71]
	v_pk_mul_f32 v[24:25], v[48:49], v[68:69]
	s_nop 0
	v_cvt_pk_bf16_f32 v36, v24, v25
	v_cvt_pk_bf16_f32 v37, v26, v27
	ds_write_b64 v55, v[36:37] offset:96
	ds_read2st64_b32 v[36:37], v38 offset1:2
	ds_read2st64_b32 v[38:39], v38 offset0:4 offset1:6
	v_add3_u32 v55, s46, v227, v54
	s_waitcnt lgkmcnt(1)
	v_mov_b32_e32 v48, v36
	s_waitcnt lgkmcnt(0)
	v_mov_b32_e32 v49, v38
	v_mov_b32_e32 v38, v37
	v_pk_add_f32 v[36:37], v[48:49], v[38:39]
	s_nop 0
	v_add_f32_e32 v36, v36, v37
	v_fmamk_f32 v36, v36, 0x3b800000, v53
	v_mul_f32_e32 v37, 0x4b800000, v36
	v_cmp_gt_f32_e32 vcc, s0, v36
	s_nop 1
	v_cndmask_b32_e32 v36, v36, v37, vcc
	v_rsq_f32_e32 v36, v36
	s_nop 0
	v_mul_f32_e32 v37, 0x45800000, v36
	v_cndmask_b32_e32 v36, v36, v37, vcc
	v_pk_mul_f32 v[38:39], v[110:111], v[36:37] op_sel_hi:[1,0]
	v_pk_mul_f32 v[48:49], v[108:109], v[36:37] op_sel_hi:[1,0]
	v_pk_mul_f32 v[50:51], v[98:99], v[36:37] op_sel_hi:[1,0]
	v_pk_mul_f32 v[46:47], v[46:47], v[36:37] op_sel_hi:[1,0]
	v_pk_mul_f32 v[44:45], v[44:45], v[36:37] op_sel_hi:[1,0]
	v_pk_mul_f32 v[42:43], v[42:43], v[36:37] op_sel_hi:[1,0]
	s_waitcnt vmcnt(0)
	v_pk_mul_f32 v[26:27], v[58:59], v[48:49]
	v_pk_mul_f32 v[24:25], v[56:57], v[38:39]
	v_pk_mul_f32 v[48:49], v[102:103], v[36:37] op_sel_hi:[1,0]
	v_cvt_pk_bf16_f32 v38, v24, v25
	v_cvt_pk_bf16_f32 v39, v26, v27
	ds_write_b64 v55, v[38:39]
	v_pk_mul_f32 v[36:37], v[40:41], v[36:37] op_sel_hi:[1,0]
	s_waitcnt vmcnt(0)
	v_pk_mul_f32 v[26:27], v[62:63], v[50:51]
	v_pk_mul_f32 v[24:25], v[60:61], v[48:49]
	s_nop 0
	v_cvt_pk_bf16_f32 v38, v24, v25
	v_cvt_pk_bf16_f32 v39, v26, v27
	ds_write_b64 v55, v[38:39] offset:32
	s_waitcnt vmcnt(0)
	v_pk_mul_f32 v[26:27], v[66:67], v[44:45]
	v_pk_mul_f32 v[24:25], v[64:65], v[46:47]
	s_nop 0
	v_cvt_pk_bf16_f32 v38, v24, v25
	v_cvt_pk_bf16_f32 v39, v26, v27
	ds_write_b64 v55, v[38:39] offset:64
	v_lshl_add_u32 v38, v212, 2, s49
	s_waitcnt vmcnt(0)
; #define LAS __attribute__((address_space(3)))
; __device__ __forceinline__ unsigned cvt_pk_bf16(float lo, float hi) { unsigned r; asm volatile("v_cvt_pk_bf16_f32 %0, %1, %2" : "=v"(r) : "v"(lo), "v"(hi)); return r; }
; __device__ void passB_unit(const Params& p, LAS unsigned char* lds, int u, bool do_store = true) {
;     ...
; #pragma unroll
;     for (int mt = 0; mt < 4; ++mt) { const int t = wt2 * 64 + mt * 16 + fr;
;         const float tot = (ssP[t] + ssP[128 + t]) + (ssP[256 + t] + ssP[384 + t]); const float rinv = rsqrtf(tot * (1.0f / 256.0f) + 1e-6f);
; #pragma unroll
;         for (int nt = 0; nt < 4; ++nt) { const int v = w4 * 64 + nt * 16 + fq * 4; const f32x4 hw = *(const f32x4*)(p.head_norm_w + h * 256 + v);
;             const f32x4 o = hsum[mt][nt] * rinv * hw;
;             u32x2 w; w.x = cvt_pk_bf16(o[0], o[1]); w.y = cvt_pk_bf16(o[2], o[3]);
;             *(LAS u32x2*)(Pd + t * 264 + v) = w; } }
	v_pk_mul_f32 v[26:27], v[36:37], v[70:71]
	v_pk_mul_f32 v[24:25], v[42:43], v[68:69]
	s_nop 0
	v_cvt_pk_bf16_f32 v36, v24, v25
	v_cvt_pk_bf16_f32 v37, v26, v27
	ds_write_b64 v55, v[36:37] offset:96
	ds_read2st64_b32 v[36:37], v38 offset1:2
	ds_read2st64_b32 v[38:39], v38 offset0:4 offset1:6
	s_waitcnt lgkmcnt(1)
	v_mov_b32_e32 v40, v36
	s_waitcnt lgkmcnt(0)
	v_mov_b32_e32 v41, v38
	v_mov_b32_e32 v38, v37
	v_pk_add_f32 v[36:37], v[40:41], v[38:39]
	s_nop 0
	v_add_f32_e32 v36, v36, v37
	v_fmamk_f32 v36, v36, 0x3b800000, v53
	v_mul_f32_e32 v37, 0x4b800000, v36
	v_cmp_gt_f32_e32 vcc, s0, v36
	s_nop 1
	v_cndmask_b32_e32 v36, v36, v37, vcc
	v_rsq_f32_e32 v36, v36
	s_nop 0
	v_mul_f32_e32 v37, 0x45800000, v36
	v_cndmask_b32_e32 v36, v36, v37, vcc
	v_pk_mul_f32 v[32:33], v[32:33], v[36:37] op_sel_hi:[1,0]
	v_pk_mul_f32 v[34:35], v[34:35], v[36:37] op_sel_hi:[1,0]
	v_pk_mul_f32 v[22:23], v[22:23], v[36:37] op_sel_hi:[1,0]
	v_pk_mul_f32 v[20:21], v[20:21], v[36:37] op_sel_hi:[1,0]
	v_pk_mul_f32 v[18:19], v[18:19], v[36:37] op_sel_hi:[1,0]
	v_pk_mul_f32 v[14:15], v[14:15], v[36:37] op_sel_hi:[1,0]
	v_pk_mul_f32 v[10:11], v[10:11], v[36:37] op_sel_hi:[1,0]
	v_pk_mul_f32 v[8:9], v[8:9], v[36:37] op_sel_hi:[1,0]
	s_waitcnt vmcnt(0)
	v_pk_mul_f32 v[26:27], v[58:59], v[34:35]
	v_pk_mul_f32 v[24:25], v[56:57], v[32:33]
	v_add3_u32 v34, s46, v223, v54
	v_cvt_pk_bf16_f32 v32, v24, v25
	v_cvt_pk_bf16_f32 v33, v26, v27
	ds_write_b64 v34, v[32:33]
	s_waitcnt vmcnt(0)
	v_pk_mul_f32 v[20:21], v[62:63], v[20:21]
	v_pk_mul_f32 v[22:23], v[60:61], v[22:23]
	s_nop 0
	v_cvt_pk_bf16_f32 v24, v22, v23
	v_cvt_pk_bf16_f32 v25, v20, v21
	ds_write_b64 v34, v[24:25] offset:32
	s_waitcnt vmcnt(0)
	v_pk_mul_f32 v[18:19], v[64:65], v[18:19]
	v_pk_mul_f32 v[14:15], v[66:67], v[14:15]
	v_cvt_pk_bf16_f32 v22, v18, v19
	s_nop 0
	v_cvt_pk_bf16_f32 v23, v14, v15
	ds_write_b64 v34, v[22:23] offset:64
	s_waitcnt vmcnt(0)
	v_pk_mul_f32 v[8:9], v[8:9], v[70:71]
	v_pk_mul_f32 v[10:11], v[10:11], v[68:69]
	v_lshl_add_u32 v18, v213, 2, s49
	v_cvt_pk_bf16_f32 v14, v10, v11
	v_cvt_pk_bf16_f32 v15, v8, v9
	ds_write_b64 v34, v[14:15] offset:96
	ds_read2st64_b32 v[14:15], v18 offset1:2
	ds_read2st64_b32 v[18:19], v18 offset0:4 offset1:6
	s_waitcnt lgkmcnt(1)
	v_mov_b32_e32 v20, v14
	s_waitcnt lgkmcnt(0)
	v_mov_b32_e32 v21, v18
	v_mov_b32_e32 v18, v15
	v_pk_add_f32 v[14:15], v[20:21], v[18:19]
	s_nop 0
	v_add_f32_e32 v14, v14, v15
	v_fmac_f32_e32 v53, 0x3b800000, v14
	v_mul_f32_e32 v14, 0x4b800000, v53
	v_cmp_gt_f32_e32 vcc, s0, v53
	s_mov_b32 s0, 0
	s_nop 0
	v_cndmask_b32_e32 v14, v53, v14, vcc
	v_rsq_f32_e32 v14, v14
	s_nop 0
	v_mul_f32_e32 v15, 0x45800000, v14
	v_cndmask_b32_e32 v14, v14, v15, vcc
	v_pk_mul_f32 v[18:19], v[28:29], v[14:15] op_sel_hi:[1,0]
	v_pk_mul_f32 v[20:21], v[30:31], v[14:15] op_sel_hi:[1,0]
	v_add3_u32 v15, s46, v222, v54
	v_pk_mul_f32 v[16:17], v[16:17], v[14:15] op_sel_hi:[1,0]
	v_pk_mul_f32 v[6:7], v[6:7], v[14:15] op_sel_hi:[1,0]
	v_pk_mul_f32 v[12:13], v[12:13], v[14:15] op_sel_hi:[1,0]
	v_pk_mul_f32 v[4:5], v[4:5], v[14:15] op_sel_hi:[1,0]
	v_pk_mul_f32 v[2:3], v[2:3], v[14:15] op_sel_hi:[1,0]
	v_pk_mul_f32 v[0:1], v[0:1], v[14:15] op_sel_hi:[1,0]
	s_waitcnt vmcnt(0)
	v_pk_mul_f32 v[10:11], v[58:59], v[20:21]
	v_pk_mul_f32 v[8:9], v[56:57], v[18:19]
	s_nop 0
	v_cvt_pk_bf16_f32 v18, v8, v9
	v_cvt_pk_bf16_f32 v19, v10, v11
	ds_write_b64 v15, v[18:19]
	s_waitcnt vmcnt(0)
	v_pk_mul_f32 v[6:7], v[62:63], v[6:7]
	v_pk_mul_f32 v[8:9], v[60:61], v[16:17]
	s_nop 0
	v_cvt_pk_bf16_f32 v10, v8, v9
	v_cvt_pk_bf16_f32 v11, v6, v7
	ds_write_b64 v15, v[10:11] offset:32
	s_waitcnt vmcnt(0)
	v_pk_mul_f32 v[4:5], v[66:67], v[4:5]
	v_pk_mul_f32 v[6:7], v[64:65], v[12:13]
	s_nop 0
	v_cvt_pk_bf16_f32 v8, v6, v7
	v_cvt_pk_bf16_f32 v9, v4, v5
	ds_write_b64 v15, v[8:9] offset:64
	s_waitcnt vmcnt(0)
	v_pk_mul_f32 v[0:1], v[0:1], v[70:71]
	v_pk_mul_f32 v[2:3], v[2:3], v[68:69]
	s_nop 0
	v_cvt_pk_bf16_f32 v2, v2, v3
	v_cvt_pk_bf16_f32 v3, v0, v1
	ds_write_b64 v15, v[2:3] offset:96
	s_waitcnt lgkmcnt(0)
	s_barrier
	v_or_b32_e32 v2, v198, v199
	v_add_u32_e32 v0, s46, v203
	v_or_b32_e32 v1, v202, v201
	s_mov_b32 s1, 0xfffffc0
	s_movk_i32 s4, 0x210
	v_lshlrev_b32_e32 v2, 6, v2
